# long conv L=16384 inner loop: K-chunk re-association (lane half hh holds chunk c+4hh) so each u-window fragment feeds both accumulators: 9 ds_read_b128 per 8 MFMA instead of 12
# speedup vs baseline: 1.0099x; 1.0099x over previous
; #define LAS __attribute__((address_space(3)))
; #define CONV_KEEP(k_) asm volatile("" :: "v"(fa[k_][0]), "v"(fb0[k_][0]), "v"(fb1[k_][0]), "v"(fa[k_][1]), "v"(fb0[k_][1]), "v"(fb1[k_][1]))
; template <int L, int NB>
; DI void conv_unit(const Frame& F, int c, const bf16* FRg, const float* F0, const float* hyD, const bf16* UT, bf16* YT, int tok0, bool dry) {
;     ...
;     const int jj = r32 % JB, bb = r32 / JB;
;     const int xA0 = L - RS * r32 + 8 * hh - RS;
;     const LAS unsigned char* ubp0 = uw + bb * BST + hh * WN + 16 * jj;
;     const LAS unsigned char* ubp1 = uw + bb * BST + (1 - hh) * WN + 16 * (jj + hh);
;     ...
;         bf16x8 fa[3][2], fb0[3][2], fb1[3][2];
;         fa[2][0] = (bf16x8){0, 0, 0, 0, 0, 0, 0, 0}; fa[2][1] = fa[2][0]; fb0[2][0] = fa[2][0]; fb0[2][1] = fa[2][0]; fb1[2][0] = fa[2][0]; fb1[2][1] = fa[2][0];
;         CONV_GLD(0, 0); CONV_GLD(1, 1);
;         const int ng = nst >> 1;
;         int g = 0;
;         for (; g + 3 < ng; g += 3) {
;             CONV_MM(0); CONV_KEEP(2); CONV_GLD(2, g + 2);
;             CONV_MM(1); CONV_KEEP(0); CONV_GLD(0, g + 3);
;             CONV_MM(2); CONV_KEEP(1); CONV_GLD(1, g + 4);
;         }
;         CONV_MM(0); CONV_KEEP(2); CONV_GLD(2, g + 2);
;         CONV_MM(1); CONV_KEEP(0);
;         CONV_MM(2); CONV_KEEP(1);
;         CONV_KEEP(2);
.LBB0_993:
	s_mul_i32 s27, s52, 0x780
	v_lshrrev_b32_e32 v240, 5, v148
	v_mul_u32_u24_e32 v241, 24, v240
	v_add3_u32 v3, v166, s27, v241
	v_mul_u32_u24_e32 v241, 0x9e0, v240
	v_sub_u32_e32 v1, v228, v241
	v_add_u32_e32 v2, 0xa00, v1
	s_lshr_b32 s27, s26, 2
	v_ashrrev_i32_e32 v239, 5, v3
	v_and_b32_e32 v239, -16, v239
	v_lshl_add_u32 v239, v3, 1, v239
	v_add_u32_e32 v240, 64, v3
	v_ashrrev_i32_e32 v241, 5, v240
	v_and_b32_e32 v241, -16, v241
	v_lshl_add_u32 v241, v240, 1, v241
	ds_read_b128 v[76:79], v239
	ds_read_b128 v[92:95], v1
	ds_read_b128 v[80:83], v239 offset:16
	ds_read_b128 v[96:99], v2
	ds_read_b128 v[84:87], v239 offset:32
	ds_read_b128 v[100:103], v1 offset:16
	ds_read_b128 v[88:91], v239 offset:48
	ds_read_b128 v[104:107], v2 offset:16
	ds_read_b128 v[108:111], v1 offset:32
	ds_read_b128 v[112:115], v241
	ds_read_b128 v[128:131], v1 offset:64
	ds_read_b128 v[116:119], v241 offset:16
	ds_read_b128 v[132:135], v2 offset:64
	ds_read_b128 v[120:123], v241 offset:32
	ds_read_b128 v[136:139], v1 offset:80
	ds_read_b128 v[124:127], v241 offset:48
	ds_read_b128 v[140:143], v2 offset:80
	ds_read_b128 v[144:147], v1 offset:96
	v_add_u32_e32 v3, 0x80, v3
	v_add_u32_e32 v1, 0x80, v1
	v_add_u32_e32 v2, 0x80, v2
	s_add_i32 s27, s27, -1
.Lc16_loop:
	v_ashrrev_i32_e32 v239, 5, v3
	v_and_b32_e32 v239, -16, v239
	v_lshl_add_u32 v239, v3, 1, v239
	v_add_u32_e32 v240, 64, v3
	v_ashrrev_i32_e32 v241, 5, v240
	v_and_b32_e32 v241, -16, v241
	v_lshl_add_u32 v241, v240, 1, v241
	s_waitcnt lgkmcnt(9)
	v_mfma_f32_32x32x16_bf16 v[20:35], v[76:79], v[92:95], v[20:35]
	v_mfma_f32_32x32x16_bf16 v[4:19], v[76:79], v[96:99], v[4:19]
	ds_read_b128 v[76:79], v239
	ds_read_b128 v[92:95], v1
	v_mfma_f32_32x32x16_bf16 v[20:35], v[80:83], v[96:99], v[20:35]
	v_mfma_f32_32x32x16_bf16 v[4:19], v[80:83], v[100:103], v[4:19]
	ds_read_b128 v[80:83], v239 offset:16
	ds_read_b128 v[96:99], v2
	v_mfma_f32_32x32x16_bf16 v[20:35], v[84:87], v[100:103], v[20:35]
	v_mfma_f32_32x32x16_bf16 v[4:19], v[84:87], v[104:107], v[4:19]
	ds_read_b128 v[84:87], v239 offset:32
	ds_read_b128 v[100:103], v1 offset:16
	v_mfma_f32_32x32x16_bf16 v[20:35], v[88:91], v[104:107], v[20:35]
	v_mfma_f32_32x32x16_bf16 v[4:19], v[88:91], v[108:111], v[4:19]
	ds_read_b128 v[88:91], v239 offset:48
	ds_read_b128 v[104:107], v2 offset:16
	ds_read_b128 v[108:111], v1 offset:32
	s_waitcnt lgkmcnt(9)
	v_mfma_f32_32x32x16_bf16 v[20:35], v[112:115], v[128:131], v[20:35]
	v_mfma_f32_32x32x16_bf16 v[4:19], v[112:115], v[132:135], v[4:19]
	ds_read_b128 v[112:115], v241
	ds_read_b128 v[128:131], v1 offset:64
	v_mfma_f32_32x32x16_bf16 v[20:35], v[116:119], v[132:135], v[20:35]
	v_mfma_f32_32x32x16_bf16 v[4:19], v[116:119], v[136:139], v[4:19]
	ds_read_b128 v[116:119], v241 offset:16
	ds_read_b128 v[132:135], v2 offset:64
	v_mfma_f32_32x32x16_bf16 v[20:35], v[120:123], v[136:139], v[20:35]
	v_mfma_f32_32x32x16_bf16 v[4:19], v[120:123], v[140:143], v[4:19]
	ds_read_b128 v[120:123], v241 offset:32
	ds_read_b128 v[136:139], v1 offset:80
	v_mfma_f32_32x32x16_bf16 v[20:35], v[124:127], v[140:143], v[20:35]
	v_mfma_f32_32x32x16_bf16 v[4:19], v[124:127], v[144:147], v[4:19]
	ds_read_b128 v[124:127], v241 offset:48
	ds_read_b128 v[140:143], v2 offset:80
	ds_read_b128 v[144:147], v1 offset:96
	v_add_u32_e32 v3, 0x80, v3
	v_add_u32_e32 v1, 0x80, v1
	v_add_u32_e32 v2, 0x80, v2
	s_add_i32 s27, s27, -1
	s_cmp_lg_u32 s27, 0
	s_cbranch_scc1 .Lc16_loop
	s_waitcnt lgkmcnt(9)
	v_mfma_f32_32x32x16_bf16 v[20:35], v[76:79], v[92:95], v[20:35]
	v_mfma_f32_32x32x16_bf16 v[4:19], v[76:79], v[96:99], v[4:19]
	v_mfma_f32_32x32x16_bf16 v[20:35], v[80:83], v[96:99], v[20:35]
	v_mfma_f32_32x32x16_bf16 v[4:19], v[80:83], v[100:103], v[4:19]
	v_mfma_f32_32x32x16_bf16 v[20:35], v[84:87], v[100:103], v[20:35]
	v_mfma_f32_32x32x16_bf16 v[4:19], v[84:87], v[104:107], v[4:19]
	v_mfma_f32_32x32x16_bf16 v[20:35], v[88:91], v[104:107], v[20:35]
	v_mfma_f32_32x32x16_bf16 v[4:19], v[88:91], v[108:111], v[4:19]
	s_waitcnt lgkmcnt(0)
	v_add_u32_e32 v238, 0xf00, v238
	v_add_u32_e32 v237, 0x780, v237
	s_cmp_eq_u32 s28, 9
	v_mfma_f32_32x32x16_bf16 v[20:35], v[112:115], v[128:131], v[20:35]
	v_mfma_f32_32x32x16_bf16 v[4:19], v[112:115], v[132:135], v[4:19]
	v_mfma_f32_32x32x16_bf16 v[20:35], v[116:119], v[132:135], v[20:35]
	v_mfma_f32_32x32x16_bf16 v[4:19], v[116:119], v[136:139], v[4:19]
	v_mfma_f32_32x32x16_bf16 v[20:35], v[120:123], v[136:139], v[20:35]
	v_mfma_f32_32x32x16_bf16 v[4:19], v[120:123], v[140:143], v[4:19]
	v_mfma_f32_32x32x16_bf16 v[20:35], v[124:127], v[140:143], v[20:35]
	v_mfma_f32_32x32x16_bf16 v[4:19], v[124:127], v[144:147], v[4:19]
	s_cbranch_scc1 .LBB0_997
	s_mov_b32 s52, s28
	s_branch .LBB0_901
